# instruction selection: GEMM accumulator zeroing between tiles with 64 v_mov_b64 instead of 128 v_mov_b32
# baseline (speedup 1.0000x reference)
; __device__ __forceinline__ void gemm_phase(LAS unsigned char* lds, const Gemm g, const StaticOrder& S, const Epi& E, const int tid) {
;     ...
;     for (int t = 0; t < nt; t += 2) {
;       const bool last = (t == nt - 2);
;       const char* a1 = cA + (size_t)(t + 1) * kstep;
;       const char* a2 = last ? nA : cA + (size_t)(t + 2) * kstep; const char* b2 = last ? nB : cB + (size_t)(t + 2) * kstep;
;     ...
;     for (int a = 0; a < 2; ++a)
; #pragma unroll
;       for (int b = 0; b < 2; ++b)
; #pragma unroll
;         for (int m = 0; m < 4; ++m)
; #pragma unroll
;           for (int n = 0; n < 2; ++n) acc[a][b][m][n] = (f32x4){0.f, 0.f, 0.f, 0.f};
;     cur = nxt; cA = nA; cB = nB; ++ui;
.LBB0_297:
	v_mov_b64_e32 v[0:1], 0
	v_mov_b64_e32 v[2:3], 0
	v_mov_b64_e32 v[4:5], 0
	v_mov_b64_e32 v[6:7], 0
	v_mov_b64_e32 v[8:9], 0
	v_mov_b64_e32 v[10:11], 0
	v_mov_b64_e32 v[12:13], 0
	v_mov_b64_e32 v[14:15], 0
	v_mov_b64_e32 v[16:17], 0
	v_mov_b64_e32 v[18:19], 0
	v_mov_b64_e32 v[20:21], 0
	v_mov_b64_e32 v[22:23], 0
	v_mov_b64_e32 v[24:25], 0
	v_mov_b64_e32 v[26:27], 0
	v_mov_b64_e32 v[28:29], 0
	v_mov_b64_e32 v[30:31], 0
	v_mov_b64_e32 v[32:33], 0
	v_mov_b64_e32 v[34:35], 0
	v_mov_b64_e32 v[36:37], 0
	v_mov_b64_e32 v[38:39], 0
	v_mov_b64_e32 v[40:41], 0
	v_mov_b64_e32 v[42:43], 0
	v_mov_b64_e32 v[44:45], 0
	v_mov_b64_e32 v[46:47], 0
	v_mov_b64_e32 v[48:49], 0
	v_mov_b64_e32 v[50:51], 0
	v_mov_b64_e32 v[52:53], 0
	v_mov_b64_e32 v[54:55], 0
	v_mov_b64_e32 v[56:57], 0
	v_mov_b64_e32 v[58:59], 0
	v_mov_b64_e32 v[60:61], 0
	v_mov_b64_e32 v[62:63], 0
	v_mov_b64_e32 v[64:65], 0
	v_mov_b64_e32 v[66:67], 0
	v_mov_b64_e32 v[68:69], 0
	v_mov_b64_e32 v[70:71], 0
	v_mov_b64_e32 v[72:73], 0
	v_mov_b64_e32 v[74:75], 0
	v_mov_b64_e32 v[76:77], 0
	v_mov_b64_e32 v[78:79], 0
	v_mov_b64_e32 v[80:81], 0
	v_mov_b64_e32 v[82:83], 0
	v_mov_b64_e32 v[84:85], 0
	v_mov_b64_e32 v[86:87], 0
	v_mov_b64_e32 v[88:89], 0
	v_mov_b64_e32 v[90:91], 0
	v_mov_b64_e32 v[92:93], 0
	v_mov_b64_e32 v[94:95], 0
	v_mov_b64_e32 v[96:97], 0
	v_mov_b64_e32 v[98:99], 0
	v_mov_b64_e32 v[100:101], 0
	v_mov_b64_e32 v[102:103], 0
	v_mov_b64_e32 v[104:105], 0
	v_mov_b64_e32 v[106:107], 0
	v_mov_b64_e32 v[108:109], 0
	v_mov_b64_e32 v[110:111], 0
	v_mov_b64_e32 v[112:113], 0
	v_mov_b64_e32 v[114:115], 0
	v_mov_b64_e32 v[116:117], 0
	v_mov_b64_e32 v[118:119], 0
	v_mov_b64_e32 v[120:121], 0
	v_mov_b64_e32 v[122:123], 0
	v_mov_b64_e32 v[124:125], 0
	v_mov_b64_e32 v[126:127], 0
	s_andn2_b64 vcc, exec, s[46:47]
	s_cbranch_vccnz .LBB0_300
	s_add_u32 vcc_lo, s68, 0x100
	s_addc_u32 vcc_hi, s69, 0
	s_add_u32 s8, s70, 0x80
	s_addc_u32 s9, s71, 0
	s_mov_b32 s10, 0
	s_mov_b64 s[2:3], 0x80
